# transpose-loop loads of hg M1/M3 issued at unit entry, ret M1/M3 both trips issued together
# baseline (speedup 1.0000x reference)
.LBB0_649:
	s_andn2_b64 vcc, exec, s[42:43]
	s_cbranch_vccnz .LBB0_674
	s_and_b32 s45, s88, 3
	v_mov_b32_e32 v66, v186
	s_lshl_b32 s100, s44, 6
	v_and_b32_e32 v100, 63, v66
	v_or_b32_e32 v100, s100, v100
	v_mov_b64_e32 v[102:103], s[48:49]
	v_mad_u64_u32 v[102:103], vcc, v100, s13, v[102:103]
	s_mul_i32 s101, s45, 0xc0
	s_add_i32 s101, s101, 0x1400
	v_lshrrev_b32_e32 v104, 6, v66
	v_lshl_add_u32 v104, v104, 4, s101
	v_mov_b32_e32 v105, 0
	v_lshl_add_u64 v[102:103], v[102:103], 0, v[104:105]
	global_load_dwordx4 v[110:113], v[102:103], off
	global_load_dwordx4 v[114:117], v[102:103], off offset:128
	s_lshl_b32 s6, s45, 7
	s_mov_b64 s[42:43], -1
	s_and_b64 vcc, exec, s[4:5]
	v_lshlrev_b32_e32 v1, 3, v66
	s_cbranch_vccz .LBB0_652
	s_lshl_b32 s10, s6, 2
	v_readlane_b32 s11, v255, 31
	v_lshlrev_b32_e32 v0, 3, v66
	s_add_u32 s10, s11, s10
	v_readlane_b32 s11, v255, 32
	v_and_b32_e32 v140, 0x78, v0
	s_addc_u32 s11, s11, 0
	v_lshlrev_b32_e32 v2, 2, v140
	s_nop 1
	global_load_dwordx4 v[20:23], v2, s[10:11] offset:16
	global_load_dwordx4 v[24:27], v2, s[10:11]
	s_mov_b64 s[42:43], 0
	v_mov_b32_e32 v68, v140

.LBB0_654:
	s_lshl_b32 s10, s44, 2
	s_add_i32 s10, s88, s10
	s_add_i32 s12, s10, -4
	s_ashr_i32 s10, s12, 2
	s_ashr_i32 s11, s10, 31
	s_lshl_b64 s[46:47], s[10:11], 6
	s_mul_hi_i32 s11, s12, 0x6000
	s_mulk_i32 s12, 0x6000
	s_add_u32 s10, s33, s12
	s_addc_u32 s11, s57, s11
	v_lshlrev_b64 v[46:47], 1, v[140:141]
	v_and_b32_e32 v0, 0xffffff80, v0
	v_lshl_add_u64 v[2:3], s[10:11], 0, v[46:47]
	v_ashrrev_i32_e32 v1, 31, v0
	v_lshl_add_u64 v[4:5], v[0:1], 1, v[2:3]
	global_load_dwordx4 v[12:15], v[4:5], off
	v_add_u32_e32 v4, 0x1000, v0
	v_add_u32_e32 v0, 0x2000, v0
	v_ashrrev_i32_e32 v32, 3, v66
	v_ashrrev_i32_e32 v5, 31, v4
	v_ashrrev_i32_e32 v1, 31, v0
	v_ashrrev_i32_e32 v33, 31, v32
	v_lshl_add_u64 v[4:5], v[4:5], 1, v[2:3]
	v_lshl_add_u64 v[0:1], v[0:1], 1, v[2:3]
	v_lshl_add_u64 v[30:31], s[46:47], 0, v[32:33]
	v_mov_b64_e32 v[48:49], s[48:49]
	s_mulk_i32 s45, 0x60
	global_load_dwordx4 v[8:11], v[4:5], off
	v_and_b32_e32 v2, 7, v66
	global_load_dwordx4 v[4:7], v[0:1], off
	v_mad_u64_u32 v[0:1], s[10:11], v30, s13, v[48:49]
	v_mad_i32_i24 v1, v31, s13, v1
	s_lshl_b32 s60, s45, 1
	v_mul_u32_u24_e32 v33, 12, v2
	v_lshl_add_u64 v[0:1], v[0:1], 0, s[60:61]
	v_lshlrev_b32_e32 v140, 1, v33
	v_lshl_add_u64 v[0:1], v[0:1], 0, v[140:141]
	s_mov_b64 s[10:11], 0x1700
	s_movk_i32 s12, 0x1000
	v_lshl_add_u64 v[16:17], v[0:1], 0, s[10:11]
	v_add_co_u32_e32 v0, vcc, s12, v0
	v_ashrrev_i32_e32 v34, 4, v66
	s_nop 0
	v_addc_co_u32_e32 v1, vcc, 0, v1, vcc
	v_ashrrev_i32_e32 v35, 31, v34
	global_load_dwordx4 v[0:3], v[0:1], off offset:1792
	s_nop 0
	global_load_dwordx2 v[28:29], v[16:17], off offset:16
	v_lshl_add_u64 v[16:17], s[46:47], 0, v[34:35]
	v_mad_u64_u32 v[18:19], s[10:11], v16, s13, v[48:49]
	v_mad_i32_i24 v19, v17, s13, v19
	s_lshl_b32 s86, s6, 1
	s_mov_b32 s87, s61
	v_lshl_add_u64 v[16:17], v[18:19], 0, s[86:87]
	v_lshl_add_u64 v[16:17], v[16:17], 0, v[46:47]
	v_add_co_u32_e32 v18, vcc, s12, v16
	s_waitcnt vmcnt(0)
	v_pk_add_f32 v[50:51], v[24:25], 1.0 op_sel_hi:[1,0] neg_lo:[1,0] neg_hi:[1,0]
	v_addc_co_u32_e32 v19, vcc, 0, v17, vcc
	global_load_dwordx4 v[36:39], v[18:19], off
	v_pk_add_f32 v[52:53], v[26:27], 1.0 op_sel_hi:[1,0] neg_lo:[1,0] neg_hi:[1,0]
	v_lshl_add_u32 v67, v68, 2, 0
	v_lshlrev_b32_e32 v35, 9, v34
	v_add_u32_e32 v35, v67, v35
	s_movk_i32 s6, 0x300
	s_waitcnt vmcnt(0)
	v_lshlrev_b32_e32 v18, 16, v36
	v_and_b32_e32 v19, 0xffff0000, v36
	v_mul_f32_e32 v18, 0xbfb8aa3b, v18
	v_mul_f32_e32 v19, 0xbfb8aa3b, v19
	v_exp_f32_e32 v18, v18
	v_exp_f32_e32 v19, v19
	v_lshlrev_b32_e32 v42, 16, v37
	v_and_b32_e32 v43, 0xffff0000, v37
	v_lshlrev_b32_e32 v44, 16, v38
	v_pk_add_f32 v[18:19], v[18:19], 1.0 op_sel_hi:[1,0]
	v_and_b32_e32 v45, 0xffff0000, v38
	v_div_scale_f32 v36, s[10:11], v19, v19, 1.0
	v_rcp_f32_e32 v37, v36
	v_lshlrev_b32_e32 v56, 16, v39
	v_and_b32_e32 v60, 0xffff0000, v39
	v_fma_f32 v38, -v36, v37, 1.0
	v_fmac_f32_e32 v37, v38, v37
	v_div_scale_f32 v38, vcc, 1.0, v19, 1.0
	v_mul_f32_e32 v39, v38, v37
	v_fma_f32 v40, -v36, v39, v38
	v_fmac_f32_e32 v39, v40, v37
	v_fma_f32 v36, -v36, v39, v38
	v_div_fmas_f32 v36, v36, v37, v39
	v_div_fixup_f32 v19, v36, v19, 1.0
	v_div_scale_f32 v36, s[10:11], v18, v18, 1.0
	v_rcp_f32_e32 v37, v36
	s_nop 0
	v_fma_f32 v38, -v36, v37, 1.0
	v_fmac_f32_e32 v37, v38, v37
	v_div_scale_f32 v38, vcc, 1.0, v18, 1.0
	v_mul_f32_e32 v39, v38, v37
	v_fma_f32 v40, -v36, v39, v38
	v_fmac_f32_e32 v39, v40, v37
	v_fma_f32 v36, -v36, v39, v38
	v_div_fmas_f32 v36, v36, v37, v39
	v_div_fixup_f32 v18, v36, v18, 1.0
	v_pk_fma_f32 v[36:37], v[50:51], v[18:19], v[24:25]
	s_nop 0
	v_cmp_gt_f32_e32 vcc, s78, v36
	s_nop 1
	v_cndmask_b32_e64 v18, 0, 32, vcc
	v_ldexp_f32 v18, v36, v18
	v_log_f32_e32 v18, v18
	s_nop 0
	v_mul_f32_e32 v19, 0x3f317217, v18
	v_fma_f32 v19, v18, s20, -v19
	v_fmac_f32_e32 v19, 0x3377d1cf, v18
	v_fmac_f32_e32 v19, 0x3f317217, v18
	v_cmp_lt_f32_e64 s[42:43], |v18|, s17
	s_nop 1
	v_cndmask_b32_e64 v18, v18, v19, s[42:43]
	v_cndmask_b32_e32 v19, 0, v203, vcc
	v_cmp_gt_f32_e32 vcc, s78, v37
	v_sub_f32_e32 v40, v18, v19
	s_nop 0
	v_cndmask_b32_e64 v18, 0, 32, vcc
	v_ldexp_f32 v18, v37, v18
	v_log_f32_e32 v18, v18
	s_nop 0
	v_mul_f32_e32 v19, 0x3f317217, v18
	v_fma_f32 v19, v18, s20, -v19
	v_fmac_f32_e32 v19, 0x3377d1cf, v18
	v_fmac_f32_e32 v19, 0x3f317217, v18
	v_cmp_lt_f32_e64 s[42:43], |v18|, s17
	s_nop 1
	v_cndmask_b32_e64 v18, v18, v19, s[42:43]
	v_cndmask_b32_e32 v19, 0, v203, vcc
	v_sub_f32_e32 v41, v18, v19
	v_mul_f32_e32 v18, 0xbfb8aa3b, v42
	v_mul_f32_e32 v19, 0xbfb8aa3b, v43
	v_exp_f32_e32 v18, v18
	v_exp_f32_e32 v19, v19
	s_nop 0
	v_pk_add_f32 v[18:19], v[18:19], 1.0 op_sel_hi:[1,0]
	s_nop 0
	v_div_scale_f32 v38, s[10:11], v19, v19, 1.0
	v_rcp_f32_e32 v39, v38
	s_nop 0
	v_fma_f32 v42, -v38, v39, 1.0
	v_fmac_f32_e32 v39, v42, v39
	v_div_scale_f32 v42, vcc, 1.0, v19, 1.0
	v_mul_f32_e32 v43, v42, v39
	v_fma_f32 v54, -v38, v43, v42
	v_fmac_f32_e32 v43, v54, v39
	v_fma_f32 v38, -v38, v43, v42
	v_div_fmas_f32 v38, v38, v39, v43
	v_div_fixup_f32 v19, v38, v19, 1.0
	v_div_scale_f32 v38, s[10:11], v18, v18, 1.0
	v_rcp_f32_e32 v39, v38
	s_nop 0
	v_fma_f32 v42, -v38, v39, 1.0
	v_fmac_f32_e32 v39, v42, v39
	v_div_scale_f32 v42, vcc, 1.0, v18, 1.0
	v_mul_f32_e32 v43, v42, v39
	v_fma_f32 v54, -v38, v43, v42
	v_fmac_f32_e32 v43, v54, v39
	v_fma_f32 v38, -v38, v43, v42
	v_div_fmas_f32 v38, v38, v39, v43
	v_div_fixup_f32 v18, v38, v18, 1.0
	v_pk_fma_f32 v[38:39], v[52:53], v[18:19], v[26:27]
	v_pk_add_f32 v[54:55], v[20:21], 1.0 op_sel_hi:[1,0] neg_lo:[1,0] neg_hi:[1,0]
	v_cmp_gt_f32_e32 vcc, s78, v38
	s_nop 1
	v_cndmask_b32_e64 v18, 0, 32, vcc
	v_ldexp_f32 v18, v38, v18
	v_log_f32_e32 v18, v18
	s_nop 0
	v_mul_f32_e32 v19, 0x3f317217, v18
	v_fma_f32 v19, v18, s20, -v19
	v_fmac_f32_e32 v19, 0x3377d1cf, v18
	v_fmac_f32_e32 v19, 0x3f317217, v18
	v_cmp_lt_f32_e64 s[42:43], |v18|, s17
	s_nop 1
	v_cndmask_b32_e64 v18, v18, v19, s[42:43]
	v_cndmask_b32_e32 v19, 0, v203, vcc
	v_cmp_gt_f32_e32 vcc, s78, v39
	v_sub_f32_e32 v42, v18, v19
	s_nop 0
	v_cndmask_b32_e64 v18, 0, 32, vcc
	v_ldexp_f32 v18, v39, v18
	v_log_f32_e32 v18, v18
	s_nop 0
	v_mul_f32_e32 v19, 0x3f317217, v18
	v_fma_f32 v19, v18, s20, -v19
	v_fmac_f32_e32 v19, 0x3377d1cf, v18
	v_fmac_f32_e32 v19, 0x3f317217, v18
	v_cmp_lt_f32_e64 s[42:43], |v18|, s17
	s_nop 1
	v_cndmask_b32_e64 v18, v18, v19, s[42:43]
	v_cndmask_b32_e32 v19, 0, v203, vcc
	v_sub_f32_e32 v43, v18, v19
	v_mul_f32_e32 v18, 0xbfb8aa3b, v44
	v_mul_f32_e32 v19, 0xbfb8aa3b, v45
	v_exp_f32_e32 v18, v18
	v_exp_f32_e32 v19, v19
	ds_write_b128 v35, v[40:43]
	v_pk_add_f32 v[18:19], v[18:19], 1.0 op_sel_hi:[1,0]
	s_nop 0
	v_div_scale_f32 v40, s[10:11], v19, v19, 1.0
	v_rcp_f32_e32 v41, v40
	s_nop 0
	v_fma_f32 v42, -v40, v41, 1.0
	v_fmac_f32_e32 v41, v42, v41
	v_div_scale_f32 v42, vcc, 1.0, v19, 1.0
	v_mul_f32_e32 v43, v42, v41
	v_fma_f32 v44, -v40, v43, v42
	v_fmac_f32_e32 v43, v44, v41
	v_fma_f32 v40, -v40, v43, v42
	v_div_fmas_f32 v40, v40, v41, v43
	v_div_fixup_f32 v19, v40, v19, 1.0
	v_div_scale_f32 v40, s[10:11], v18, v18, 1.0
	v_rcp_f32_e32 v41, v40
	s_nop 0
	v_fma_f32 v42, -v40, v41, 1.0
	v_fmac_f32_e32 v41, v42, v41
	v_div_scale_f32 v42, vcc, 1.0, v18, 1.0
	v_mul_f32_e32 v43, v42, v41
	v_fma_f32 v44, -v40, v43, v42
	v_fmac_f32_e32 v43, v44, v41
	v_fma_f32 v40, -v40, v43, v42
	v_div_fmas_f32 v40, v40, v41, v43
	v_div_fixup_f32 v18, v40, v18, 1.0
	v_pk_fma_f32 v[40:41], v[54:55], v[18:19], v[20:21]
	s_nop 0
	v_cmp_gt_f32_e32 vcc, s78, v40
	s_nop 1
	v_cndmask_b32_e64 v18, 0, 32, vcc
	v_ldexp_f32 v18, v40, v18
	v_log_f32_e32 v18, v18
	s_nop 0
	v_mul_f32_e32 v19, 0x3f317217, v18
	v_fma_f32 v19, v18, s20, -v19
	v_fmac_f32_e32 v19, 0x3377d1cf, v18
	v_fmac_f32_e32 v19, 0x3f317217, v18
	v_cmp_lt_f32_e64 s[42:43], |v18|, s17
	s_nop 1
	v_cndmask_b32_e64 v18, v18, v19, s[42:43]
	v_cndmask_b32_e32 v19, 0, v203, vcc
	v_cmp_gt_f32_e32 vcc, s78, v41
	v_sub_f32_e32 v58, v18, v19
	s_nop 0
	v_cndmask_b32_e64 v18, 0, 32, vcc
	v_ldexp_f32 v18, v41, v18
	v_log_f32_e32 v18, v18
	s_nop 0
	v_mul_f32_e32 v19, 0x3f317217, v18
	v_fma_f32 v19, v18, s20, -v19
	v_fmac_f32_e32 v19, 0x3377d1cf, v18
	v_fmac_f32_e32 v19, 0x3f317217, v18
	v_cmp_lt_f32_e64 s[42:43], |v18|, s17
	s_nop 1
	v_cndmask_b32_e64 v18, v18, v19, s[42:43]
	v_cndmask_b32_e32 v19, 0, v203, vcc
	v_sub_f32_e32 v59, v18, v19
	v_mul_f32_e32 v18, 0xbfb8aa3b, v56
	v_mul_f32_e32 v19, 0xbfb8aa3b, v60
	v_exp_f32_e32 v18, v18
	v_exp_f32_e32 v19, v19
	v_pk_add_f32 v[56:57], v[22:23], 1.0 op_sel_hi:[1,0] neg_lo:[1,0] neg_hi:[1,0]
	v_pk_add_f32 v[18:19], v[18:19], 1.0 op_sel_hi:[1,0]
	s_nop 0
	v_div_scale_f32 v42, s[10:11], v19, v19, 1.0
	v_rcp_f32_e32 v43, v42
	s_nop 0
	v_fma_f32 v44, -v42, v43, 1.0
	v_fmac_f32_e32 v43, v44, v43
	v_div_scale_f32 v44, vcc, 1.0, v19, 1.0
	v_mul_f32_e32 v45, v44, v43
	v_fma_f32 v60, -v42, v45, v44
	v_fmac_f32_e32 v45, v60, v43
	v_fma_f32 v42, -v42, v45, v44
	v_div_fmas_f32 v42, v42, v43, v45
	v_div_fixup_f32 v19, v42, v19, 1.0
	v_div_scale_f32 v42, s[10:11], v18, v18, 1.0
	v_rcp_f32_e32 v43, v42
	s_nop 0
	v_fma_f32 v44, -v42, v43, 1.0
	v_fmac_f32_e32 v43, v44, v43
	v_div_scale_f32 v44, vcc, 1.0, v18, 1.0
	v_mul_f32_e32 v45, v44, v43
	v_fma_f32 v60, -v42, v45, v44
	v_fmac_f32_e32 v45, v60, v43
	v_fma_f32 v42, -v42, v45, v44
	v_div_fmas_f32 v42, v42, v43, v45
	v_div_fixup_f32 v18, v42, v18, 1.0
	v_pk_fma_f32 v[42:43], v[56:57], v[18:19], v[22:23]
	v_add_u32_e32 v44, 0x200, v66
	v_cmp_gt_f32_e32 vcc, s78, v42
	v_ashrrev_i32_e32 v44, 4, v44
	v_ashrrev_i32_e32 v45, 31, v44
	v_cndmask_b32_e64 v18, 0, 32, vcc
	v_ldexp_f32 v18, v42, v18
	v_log_f32_e32 v18, v18
	s_nop 0
	v_mul_f32_e32 v19, 0x3f317217, v18
	v_fma_f32 v19, v18, s20, -v19
	v_fmac_f32_e32 v19, 0x3377d1cf, v18
	v_fmac_f32_e32 v19, 0x3f317217, v18
	v_cmp_lt_f32_e64 s[42:43], |v18|, s17
	s_nop 1
	v_cndmask_b32_e64 v18, v18, v19, s[42:43]
	v_cndmask_b32_e32 v19, 0, v203, vcc
	v_cmp_gt_f32_e32 vcc, s78, v43
	v_sub_f32_e32 v60, v18, v19
	s_nop 0
	v_cndmask_b32_e64 v18, 0, 32, vcc
	v_ldexp_f32 v18, v43, v18
	v_log_f32_e32 v18, v18
	s_nop 0
	v_mul_f32_e32 v19, 0x3f317217, v18
	v_fma_f32 v19, v18, s20, -v19
	v_fmac_f32_e32 v19, 0x3377d1cf, v18
	v_fmac_f32_e32 v19, 0x3f317217, v18
	v_cmp_lt_f32_e64 s[42:43], |v18|, s17
	s_nop 1
	v_cndmask_b32_e64 v18, v18, v19, s[42:43]
	v_cndmask_b32_e32 v19, 0, v203, vcc
	v_sub_f32_e32 v61, v18, v19
	ds_write_b128 v35, v[58:61] offset:16
	v_lshl_add_u64 v[58:59], s[46:47], 0, v[44:45]
	v_mad_u64_u32 v[48:49], s[10:11], v58, s13, v[48:49]
	v_mad_i32_i24 v49, v59, s13, v49
	v_lshl_add_u64 v[48:49], v[48:49], 0, s[86:87]
	v_lshl_add_u64 v[58:59], v[48:49], 0, v[46:47]
	v_add_co_u32_e32 v46, vcc, s12, v58
	global_load_dwordx4 v[16:19], v[16:17], off offset:3072
	s_nop 0
	v_addc_co_u32_e32 v47, vcc, 0, v59, vcc
	global_load_dwordx4 v[46:49], v[46:47], off
	v_lshlrev_b32_e32 v45, 9, v44
	v_add_u32_e32 v45, v67, v45
	s_waitcnt vmcnt(0)
	v_lshlrev_b32_e32 v60, 16, v46
	v_and_b32_e32 v61, 0xffff0000, v46
	v_lshlrev_b32_e32 v62, 16, v47
	v_and_b32_e32 v63, 0xffff0000, v47
	v_mul_f32_e32 v46, 0xbfb8aa3b, v60
	v_mul_f32_e32 v47, 0xbfb8aa3b, v61
	v_exp_f32_e32 v46, v46
	v_exp_f32_e32 v47, v47
	v_lshlrev_b32_e32 v64, 16, v48
	v_and_b32_e32 v65, 0xffff0000, v48
	v_lshlrev_b32_e32 v69, 16, v49
	v_pk_add_f32 v[46:47], v[46:47], 1.0 op_sel_hi:[1,0]
	v_and_b32_e32 v70, 0xffff0000, v49
	v_div_scale_f32 v48, s[10:11], v47, v47, 1.0
	v_rcp_f32_e32 v49, v48
	s_nop 0
	v_fma_f32 v60, -v48, v49, 1.0
	v_fmac_f32_e32 v49, v60, v49
	v_div_scale_f32 v60, vcc, 1.0, v47, 1.0
	v_mul_f32_e32 v61, v60, v49
	v_fma_f32 v71, -v48, v61, v60
	v_fmac_f32_e32 v61, v71, v49
	v_fma_f32 v48, -v48, v61, v60
	v_div_fmas_f32 v48, v48, v49, v61
	v_div_fixup_f32 v47, v48, v47, 1.0
	v_div_scale_f32 v48, s[10:11], v46, v46, 1.0
	v_rcp_f32_e32 v49, v48
	s_nop 0
	v_fma_f32 v60, -v48, v49, 1.0
	v_fmac_f32_e32 v49, v60, v49
	v_div_scale_f32 v60, vcc, 1.0, v46, 1.0
	v_mul_f32_e32 v61, v60, v49
	v_fma_f32 v71, -v48, v61, v60
	v_fmac_f32_e32 v61, v71, v49
	v_fma_f32 v48, -v48, v61, v60
	v_div_fmas_f32 v48, v48, v49, v61
	v_div_fixup_f32 v46, v48, v46, 1.0
	v_pk_fma_f32 v[24:25], v[50:51], v[46:47], v[24:25]
	v_mul_f32_e32 v49, 0xbfb8aa3b, v63
	v_cmp_gt_f32_e32 vcc, s78, v24
	v_exp_f32_e32 v49, v49
	s_nop 0
	v_cndmask_b32_e64 v46, 0, 32, vcc
	v_ldexp_f32 v46, v24, v46
	v_log_f32_e32 v46, v46
	s_nop 0
	v_mul_f32_e32 v47, 0x3f317217, v46
	v_fma_f32 v47, v46, s20, -v47
	v_fmac_f32_e32 v47, 0x3377d1cf, v46
	v_fmac_f32_e32 v47, 0x3f317217, v46
	v_cmp_lt_f32_e64 s[42:43], |v46|, s17
	s_nop 1
	v_cndmask_b32_e64 v46, v46, v47, s[42:43]
	v_cndmask_b32_e32 v47, 0, v203, vcc
	v_cmp_gt_f32_e32 vcc, s78, v25
	v_sub_f32_e32 v46, v46, v47
	s_nop 0
	v_cndmask_b32_e64 v47, 0, 32, vcc
	v_ldexp_f32 v47, v25, v47
	v_log_f32_e32 v47, v47
	s_nop 0
	v_mul_f32_e32 v48, 0x3f317217, v47
	v_fma_f32 v48, v47, s20, -v48
	v_fmac_f32_e32 v48, 0x3377d1cf, v47
	v_fmac_f32_e32 v48, 0x3f317217, v47
	v_cmp_lt_f32_e64 s[42:43], |v47|, s17
	s_nop 1
	v_cndmask_b32_e64 v47, v47, v48, s[42:43]
	v_cndmask_b32_e32 v48, 0, v203, vcc
	v_sub_f32_e32 v47, v47, v48
	v_mul_f32_e32 v48, 0xbfb8aa3b, v62
	v_exp_f32_e32 v48, v48
	s_nop 0
	v_pk_add_f32 v[48:49], v[48:49], 1.0 op_sel_hi:[1,0]
	s_nop 0
	v_div_scale_f32 v50, s[10:11], v49, v49, 1.0
	v_rcp_f32_e32 v51, v50
	s_nop 0
	v_fma_f32 v60, -v50, v51, 1.0
	v_fmac_f32_e32 v51, v60, v51
	v_div_scale_f32 v60, vcc, 1.0, v49, 1.0
	v_mul_f32_e32 v61, v60, v51
	v_fma_f32 v62, -v50, v61, v60
	v_fmac_f32_e32 v61, v62, v51
	v_fma_f32 v50, -v50, v61, v60
	v_div_fmas_f32 v50, v50, v51, v61
	v_div_fixup_f32 v49, v50, v49, 1.0
	v_div_scale_f32 v50, s[10:11], v48, v48, 1.0
	v_rcp_f32_e32 v51, v50
	s_nop 0
	v_fma_f32 v60, -v50, v51, 1.0
	v_fmac_f32_e32 v51, v60, v51
	v_div_scale_f32 v60, vcc, 1.0, v48, 1.0
	v_mul_f32_e32 v61, v60, v51
	v_fma_f32 v62, -v50, v61, v60
	v_fmac_f32_e32 v61, v62, v51
	v_fma_f32 v50, -v50, v61, v60
	v_div_fmas_f32 v50, v50, v51, v61
	v_div_fixup_f32 v48, v50, v48, 1.0
	v_pk_fma_f32 v[26:27], v[52:53], v[48:49], v[26:27]
	s_nop 0
	v_cmp_gt_f32_e32 vcc, s78, v26
	s_nop 1
	v_cndmask_b32_e64 v48, 0, 32, vcc
	v_ldexp_f32 v48, v26, v48
	v_log_f32_e32 v48, v48
	s_nop 0
	v_mul_f32_e32 v49, 0x3f317217, v48
	v_fma_f32 v49, v48, s20, -v49
	v_fmac_f32_e32 v49, 0x3377d1cf, v48
	v_fmac_f32_e32 v49, 0x3f317217, v48
	v_cmp_lt_f32_e64 s[42:43], |v48|, s17
	s_nop 1
	v_cndmask_b32_e64 v48, v48, v49, s[42:43]
	v_cndmask_b32_e32 v49, 0, v203, vcc
	v_cmp_gt_f32_e32 vcc, s78, v27
	v_sub_f32_e32 v48, v48, v49
	s_nop 0
	v_cndmask_b32_e64 v49, 0, 32, vcc
	v_ldexp_f32 v49, v27, v49
	v_log_f32_e32 v49, v49
	s_nop 0
	v_mul_f32_e32 v50, 0x3f317217, v49
	v_fma_f32 v50, v49, s20, -v50
	v_fmac_f32_e32 v50, 0x3377d1cf, v49
	v_fmac_f32_e32 v50, 0x3f317217, v49
	v_cmp_lt_f32_e64 s[42:43], |v49|, s17
	s_nop 1
	v_cndmask_b32_e64 v49, v49, v50, s[42:43]
	v_cndmask_b32_e32 v50, 0, v203, vcc
	v_sub_f32_e32 v49, v49, v50
	ds_write_b128 v45, v[46:49]
	v_mul_f32_e32 v46, 0xbfb8aa3b, v64
	v_mul_f32_e32 v47, 0xbfb8aa3b, v65
	v_exp_f32_e32 v46, v46
	v_exp_f32_e32 v47, v47
	s_nop 0
	v_pk_add_f32 v[46:47], v[46:47], 1.0 op_sel_hi:[1,0]
	s_nop 0
	v_div_scale_f32 v48, s[10:11], v47, v47, 1.0
	v_rcp_f32_e32 v49, v48
	s_nop 0
	v_fma_f32 v50, -v48, v49, 1.0
	v_fmac_f32_e32 v49, v50, v49
	v_div_scale_f32 v50, vcc, 1.0, v47, 1.0
	v_mul_f32_e32 v51, v50, v49
	v_fma_f32 v52, -v48, v51, v50
	v_fmac_f32_e32 v51, v52, v49
	v_fma_f32 v48, -v48, v51, v50
	v_div_fmas_f32 v48, v48, v49, v51
	v_div_fixup_f32 v47, v48, v47, 1.0
	v_div_scale_f32 v48, s[10:11], v46, v46, 1.0
	v_rcp_f32_e32 v49, v48
	s_nop 0
	v_fma_f32 v50, -v48, v49, 1.0
	v_fmac_f32_e32 v49, v50, v49
	v_div_scale_f32 v50, vcc, 1.0, v46, 1.0
	v_mul_f32_e32 v51, v50, v49
	v_fma_f32 v52, -v48, v51, v50
	v_fmac_f32_e32 v51, v52, v49
	v_fma_f32 v48, -v48, v51, v50
	v_div_fmas_f32 v48, v48, v49, v51
	v_div_fixup_f32 v46, v48, v46, 1.0
	v_pk_fma_f32 v[46:47], v[54:55], v[46:47], v[20:21]
	v_mul_f32_e32 v49, 0xbfb8aa3b, v70
	v_cmp_gt_f32_e32 vcc, s78, v46
	v_exp_f32_e32 v49, v49
	s_nop 0
	v_cndmask_b32_e64 v20, 0, 32, vcc
	v_ldexp_f32 v20, v46, v20
	v_log_f32_e32 v20, v20
	s_nop 0
	v_mul_f32_e32 v21, 0x3f317217, v20
	v_fma_f32 v21, v20, s20, -v21
	v_fmac_f32_e32 v21, 0x3377d1cf, v20
	v_fmac_f32_e32 v21, 0x3f317217, v20
	v_cmp_lt_f32_e64 s[42:43], |v20|, s17
	s_nop 1
	v_cndmask_b32_e64 v20, v20, v21, s[42:43]
	v_cndmask_b32_e32 v21, 0, v203, vcc
	v_cmp_gt_f32_e32 vcc, s78, v47
	v_sub_f32_e32 v20, v20, v21
	s_nop 0
	v_cndmask_b32_e64 v21, 0, 32, vcc
	v_ldexp_f32 v21, v47, v21
	v_log_f32_e32 v21, v21
	s_nop 0
	v_mul_f32_e32 v48, 0x3f317217, v21
	v_fma_f32 v48, v21, s20, -v48
	v_fmac_f32_e32 v48, 0x3377d1cf, v21
	v_fmac_f32_e32 v48, 0x3f317217, v21
	v_cmp_lt_f32_e64 s[42:43], |v21|, s17
	s_nop 1
	v_cndmask_b32_e64 v21, v21, v48, s[42:43]
	v_cndmask_b32_e32 v48, 0, v203, vcc
	v_sub_f32_e32 v21, v21, v48
	v_mul_f32_e32 v48, 0xbfb8aa3b, v69
	v_exp_f32_e32 v48, v48
	s_nop 0
	v_pk_add_f32 v[48:49], v[48:49], 1.0 op_sel_hi:[1,0]
	s_nop 0
	v_div_scale_f32 v50, s[10:11], v49, v49, 1.0
	v_rcp_f32_e32 v51, v50
	s_nop 0
	v_fma_f32 v52, -v50, v51, 1.0
	v_fmac_f32_e32 v51, v52, v51
	v_div_scale_f32 v52, vcc, 1.0, v49, 1.0
	v_mul_f32_e32 v53, v52, v51
	v_fma_f32 v54, -v50, v53, v52
	v_fmac_f32_e32 v53, v54, v51
	v_fma_f32 v50, -v50, v53, v52
	v_div_fmas_f32 v50, v50, v51, v53
	v_div_fixup_f32 v49, v50, v49, 1.0
	v_div_scale_f32 v50, s[10:11], v48, v48, 1.0
	v_rcp_f32_e32 v51, v50
	s_nop 0
	v_fma_f32 v52, -v50, v51, 1.0
	v_fmac_f32_e32 v51, v52, v51
	v_div_scale_f32 v52, vcc, 1.0, v48, 1.0
	v_mul_f32_e32 v53, v52, v51
	v_fma_f32 v54, -v50, v53, v52
	v_fmac_f32_e32 v53, v54, v51
	v_fma_f32 v50, -v50, v53, v52
	v_div_fmas_f32 v50, v50, v51, v53
	v_div_fixup_f32 v48, v50, v48, 1.0
	v_pk_fma_f32 v[48:49], v[56:57], v[48:49], v[22:23]
	s_nop 0
	v_cmp_gt_f32_e32 vcc, s78, v48
	s_nop 1
	v_cndmask_b32_e64 v22, 0, 32, vcc
	v_ldexp_f32 v22, v48, v22
	v_log_f32_e32 v22, v22
	s_nop 0
	v_mul_f32_e32 v23, 0x3f317217, v22
	v_fma_f32 v23, v22, s20, -v23
	v_fmac_f32_e32 v23, 0x3377d1cf, v22
	v_fmac_f32_e32 v23, 0x3f317217, v22
	v_cmp_lt_f32_e64 s[42:43], |v22|, s17
	s_nop 1
	v_cndmask_b32_e64 v22, v22, v23, s[42:43]
	v_cndmask_b32_e32 v23, 0, v203, vcc
	v_cmp_gt_f32_e32 vcc, s78, v49
	v_sub_f32_e32 v22, v22, v23
	s_nop 0
	v_cndmask_b32_e64 v23, 0, 32, vcc
	v_ldexp_f32 v23, v49, v23
	v_log_f32_e32 v23, v23
	s_nop 0
	v_mul_f32_e32 v50, 0x3f317217, v23
	v_fma_f32 v50, v23, s20, -v50
	v_fmac_f32_e32 v50, 0x3377d1cf, v23
	v_fmac_f32_e32 v50, 0x3f317217, v23
	v_cmp_lt_f32_e64 s[42:43], |v23|, s17
	s_nop 1
	v_cndmask_b32_e64 v23, v23, v50, s[42:43]
	v_cndmask_b32_e32 v50, 0, v203, vcc
	v_sub_f32_e32 v23, v23, v50
	ds_write_b128 v45, v[20:23] offset:16
	global_load_dwordx4 v[20:23], v[58:59], off offset:3072
	v_cmp_gt_i32_e32 vcc, s6, v66
	s_and_saveexec_b64 s[42:43], vcc
	s_cbranch_execz .LBB0_657
	v_and_b32_e32 v52, 63, v66
	v_or_b32_e32 v53, s46, v52
	v_mov_b64_e32 v[50:51], s[48:49]
	v_mad_u64_u32 v[50:51], s[10:11], v53, s13, v[50:51]
	v_mad_i32_i24 v51, s47, v204, v51
	v_lshl_add_u64 v[50:51], v[50:51], 0, s[60:61]
	s_mov_b64 s[10:11], 0x1400
	v_readlane_b32 s6, v254, 61
	v_lshl_add_u64 v[50:51], v[50:51], 0, s[10:11]
	s_mov_b64 s[46:47], 0
	v_lshl_add_u32 v52, v52, 1, s6
	v_mov_b32_e32 v53, v66
	s_waitcnt vmcnt(0)
.LBB0_656:
	v_ashrrev_i32_e32 v54, 3, v53
	v_and_b32_e32 v58, -8, v54
	v_ashrrev_i32_e32 v59, 31, v58
	v_lshl_add_u64 v[54:55], v[58:59], 1, v[50:51]
	v_mov_b32_e32 v54, v110
	v_mov_b32_e32 v55, v111
	v_mov_b32_e32 v56, v112
	v_mov_b32_e32 v57, v113
	v_add_u32_e32 v59, 0x200, v53
	v_cmp_lt_i32_e32 vcc, s67, v53
	v_mov_b32_e32 v53, v59
	s_or_b64 s[46:47], vcc, s[46:47]
	v_mad_u64_u32 v[58:59], s[10:11], v58, s21, v[52:53]
	ds_write_b16 v58, v54
	ds_write_b16_d16_hi v58, v54 offset:144
	ds_write_b16 v58, v55 offset:288
	ds_write_b16_d16_hi v58, v55 offset:432
	ds_write_b16 v58, v56 offset:576
	ds_write_b16_d16_hi v58, v56 offset:720
	ds_write_b16 v58, v57 offset:864
	ds_write_b16_d16_hi v58, v57 offset:1008
	v_mov_b32_e32 v110, v114
	v_mov_b32_e32 v111, v115
	v_mov_b32_e32 v112, v116
	v_mov_b32_e32 v113, v117
	s_andn2_b64 exec, exec, s[46:47]
	s_cbranch_execnz .LBB0_656

.LBB0_681:
	s_or_b64 exec, exec, s[72:73]
	s_ashr_i32 s10, s10, 2
	s_ashr_i32 s11, s10, 31
	v_ashrrev_i32_e32 v44, 3, v56
	s_and_b32 s6, s88, 3
	s_lshl_b64 s[88:89], s[10:11], 6
	v_ashrrev_i32_e32 v45, 31, v44
	v_lshl_add_u64 v[42:43], s[88:89], 0, v[44:45]
	v_mov_b64_e32 v[0:1], s[48:49]
	s_mul_i32 s10, s6, 0x60
	v_mad_u64_u32 v[0:1], s[26:27], v42, s13, v[0:1]
	v_and_b32_e32 v2, 7, v56
	v_mad_i32_i24 v1, v43, s13, v1
	s_lshl_b32 s60, s10, 1
	v_mul_u32_u24_e32 v45, 12, v2
	v_lshl_add_u64 v[0:1], v[0:1], 0, s[60:61]
	v_lshlrev_b32_e32 v140, 1, v45
	v_lshl_add_u64 v[0:1], v[0:1], 0, v[140:141]
	global_load_dwordx2 v[40:41], v[0:1], off offset:2320
	s_nop 0
	global_load_dwordx4 v[0:3], v[0:1], off offset:2304
	s_movk_i32 s11, 0x300
	v_cmp_gt_i32_e64 s[46:47], s11, v56
	s_and_saveexec_b64 s[72:73], s[46:47]
	s_cbranch_execz .LBB0_684
	v_and_b32_e32 v18, 63, v56
	v_or_b32_e32 v20, s88, v18
	v_mov_b64_e32 v[16:17], s[48:49]
	v_mad_u64_u32 v[16:17], s[26:27], v20, s13, v[16:17]
	v_mad_i32_i24 v17, s89, v204, v17
	v_lshl_add_u64 v[16:17], v[16:17], 0, s[60:61]
	v_lshl_add_u32 v18, v18, 1, 0
	s_mov_b64 s[86:87], 0
	v_mov_b32_e32 v20, v56
	v_lshrrev_b32_e32 v104, 6, v56
	v_lshlrev_b32_e32 v104, 4, v104
	v_mov_b32_e32 v105, 0
	v_lshl_add_u64 v[102:103], v[16:17], 0, v[104:105]
	global_load_dwordx4 v[110:113], v[102:103], off offset:1536
	global_load_dwordx4 v[114:117], v[102:103], off offset:1664
	s_waitcnt vmcnt(0)
.LBB0_683:
	v_ashrrev_i32_e32 v21, 3, v20
	v_and_b32_e32 v26, -8, v21
	v_ashrrev_i32_e32 v27, 31, v26
	v_lshl_add_u64 v[22:23], v[26:27], 1, v[16:17]
	v_mov_b32_e32 v22, v110
	v_mov_b32_e32 v23, v111
	v_mov_b32_e32 v24, v112
	v_mov_b32_e32 v25, v113
	v_add_u32_e32 v21, 0x200, v20
	v_cmp_lt_i32_e64 s[46:47], s67, v20
	s_or_b64 s[86:87], s[46:47], s[86:87]
	v_mov_b32_e32 v20, v21
	v_mad_u64_u32 v[26:27], s[26:27], v26, s21, v[18:19]
	ds_write_b16 v26, v22 offset:51200
	ds_write_b16_d16_hi v26, v22 offset:51344
	ds_write_b16 v26, v23 offset:51488
	ds_write_b16_d16_hi v26, v23 offset:51632
	ds_write_b16 v26, v24 offset:51776
	ds_write_b16_d16_hi v26, v24 offset:51920
	ds_write_b16 v26, v25 offset:52064
	ds_write_b16_d16_hi v26, v25 offset:52208
	v_mov_b32_e32 v110, v114
	v_mov_b32_e32 v111, v115
	v_mov_b32_e32 v112, v116
	v_mov_b32_e32 v113, v117
	s_andn2_b64 exec, exec, s[86:87]
	s_cbranch_execnz .LBB0_683

.LBB0_718:
	s_and_b64 vcc, exec, s[42:43]
	s_cbranch_vccz .LBB0_731
	s_lshl_b32 s6, s77, 1
	s_add_i32 s6, s86, s6
	s_add_i32 s52, s6, -2
	v_mov_b32_e32 v36, v186
	s_and_b32 s53, s52, 3
	s_ashr_i32 s100, s52, 2
	s_lshl_b32 s100, s100, 6
	v_and_b32_e32 v100, 63, v36
	v_or_b32_e32 v100, s100, v100
	v_mov_b64_e32 v[102:103], s[48:49]
	v_mad_u64_u32 v[102:103], vcc, v100, s13, v[102:103]
	s_mul_i32 s101, s53, 0xc0
	s_add_i32 s101, s101, 0x1400
	v_lshrrev_b32_e32 v104, 6, v36
	v_lshl_add_u32 v104, v104, 4, s101
	v_mov_b32_e32 v105, 0
	v_lshl_add_u64 v[102:103], v[102:103], 0, v[104:105]
	global_load_dwordx4 v[110:113], v[102:103], off
	global_load_dwordx4 v[114:117], v[102:103], off offset:128
	s_lshl_b32 s6, s53, 7
	v_lshlrev_b32_e32 v0, 3, v36
	s_mov_b64 s[42:43], -1
	s_and_b64 vcc, exec, s[4:5]
	v_and_b32_e32 v140, 0x78, v0
	s_cbranch_vccz .LBB0_721
	s_lshl_b32 s10, s6, 2
	v_readlane_b32 s11, v255, 31
	s_add_u32 s10, s11, s10
	v_readlane_b32 s11, v255, 32
	v_and_b32_e32 v24, 0x78, v0
	s_addc_u32 s11, s11, 0
	v_lshlrev_b32_e32 v0, 2, v24
	s_nop 1
	global_load_dwordx4 v[4:7], v0, s[10:11]
	s_nop 0
	global_load_dwordx4 v[0:3], v0, s[10:11] offset:16
	v_mov_b32_e32 v25, v141
	s_mov_b64 s[42:43], 0
	v_mov_b64_e32 v[8:9], v[24:25]

.LBB0_723:
	s_ashr_i32 s10, s52, 2
	s_ashr_i32 s11, s10, 31
	v_ashrrev_i32_e32 v28, 4, v36
	s_lshl_b64 s[54:55], s[10:11], 6
	v_ashrrev_i32_e32 v29, 31, v28
	v_lshl_add_u64 v[10:11], s[54:55], 0, v[28:29]
	v_mov_b64_e32 v[14:15], s[48:49]
	v_mad_u64_u32 v[12:13], s[10:11], v10, s13, v[14:15]
	v_mad_i32_i24 v13, v11, s13, v13
	s_lshl_b32 s60, s6, 1
	v_lshl_add_u64 v[10:11], v[12:13], 0, s[60:61]
	v_lshlrev_b64 v[22:23], 1, v[8:9]
	v_lshl_add_u64 v[8:9], v[10:11], 0, v[22:23]
	s_movk_i32 s6, 0x1000
	v_add_co_u32_e32 v8, vcc, s6, v8
	v_lshlrev_b32_e32 v26, 7, v28
	s_nop 0
	v_addc_co_u32_e32 v9, vcc, 0, v9, vcc
	global_load_dwordx4 v[8:11], v[8:9], off
	s_add_i32 s58, 0, 0x10000
	s_waitcnt vmcnt(0)
	v_lshlrev_b32_e32 v12, 16, v8
	v_and_b32_e32 v8, 0xffff0000, v8
	v_lshlrev_b32_e32 v20, 16, v11
	v_and_b32_e32 v21, 0xffff0000, v11
	v_or_b32_e32 v11, v24, v26
	v_lshlrev_b32_e32 v13, 16, v9
	v_lshlrev_b32_e32 v11, 2, v11
	v_mul_f32_e32 v8, 0xbfb8aa3b, v8
	v_and_b32_e32 v9, 0xffff0000, v9
	v_add_u32_e32 v31, s58, v11
	v_add_u32_e32 v27, 0, v11
	v_exp_f32_e32 v11, v8
	v_mul_f32_e32 v8, 0xbfb8aa3b, v13
	v_lshlrev_b32_e32 v16, 16, v10
	v_and_b32_e32 v17, 0xffff0000, v10
	v_mul_f32_e32 v10, 0xbfb8aa3b, v12
	v_exp_f32_e32 v12, v8
	v_mul_f32_e32 v8, 0xbfb8aa3b, v9
	v_exp_f32_e32 v13, v8
	v_mul_f32_e32 v8, 0xbfb8aa3b, v16
	v_exp_f32_e32 v18, v8
	v_mul_f32_e32 v8, 0xbfb8aa3b, v17
	v_exp_f32_e32 v19, v8
	v_mul_f32_e32 v8, 0xbfb8aa3b, v20
	v_exp_f32_e32 v20, v8
	v_mul_f32_e32 v8, 0xbfb8aa3b, v21
	v_exp_f32_e32 v21, v8
	v_add_u32_e32 v8, 0x200, v36
	v_ashrrev_i32_e32 v32, 4, v8
	v_ashrrev_i32_e32 v33, 31, v32
	v_lshl_add_u64 v[8:9], s[54:55], 0, v[32:33]
	v_mad_u64_u32 v[14:15], s[10:11], v8, s13, v[14:15]
	v_mad_i32_i24 v15, v9, s13, v15
	v_lshl_add_u64 v[8:9], v[14:15], 0, s[60:61]
	v_lshl_add_u64 v[8:9], v[8:9], 0, v[22:23]
	v_add_co_u32_e32 v8, vcc, s6, v8
	v_exp_f32_e32 v10, v10
	s_nop 0
	v_addc_co_u32_e32 v9, vcc, 0, v9, vcc
	global_load_dwordx4 v[14:17], v[8:9], off
	v_lshlrev_b32_e32 v30, 7, v32
	v_pk_add_f32 v[10:11], v[10:11], 1.0 op_sel_hi:[1,0]
	v_pk_add_f32 v[12:13], v[12:13], 1.0 op_sel_hi:[1,0]
	s_movk_i32 s6, 0x300
	s_waitcnt vmcnt(0)
	v_lshlrev_b32_e32 v8, 16, v14
	v_and_b32_e32 v9, 0xffff0000, v14
	v_or_b32_e32 v14, v24, v30
	v_lshlrev_b32_e32 v14, 2, v14
	v_add_u32_e32 v29, s58, v14
	v_add_u32_e32 v25, 0, v14
	v_div_scale_f32 v14, s[10:11], v11, v11, 1.0
	v_lshlrev_b32_e32 v35, 16, v15
	v_and_b32_e32 v34, 0xffff0000, v15
	v_rcp_f32_e32 v15, v14
	v_lshlrev_b32_e32 v39, 16, v16
	v_and_b32_e32 v38, 0xffff0000, v16
	v_lshlrev_b32_e32 v37, 16, v17
	v_fma_f32 v40, -v14, v15, 1.0
	v_fmac_f32_e32 v15, v40, v15
	v_div_scale_f32 v40, vcc, 1.0, v11, 1.0
	v_mul_f32_e32 v41, v40, v15
	v_fma_f32 v42, -v14, v41, v40
	v_fmac_f32_e32 v41, v42, v15
	v_fma_f32 v14, -v14, v41, v40
	v_div_fmas_f32 v14, v14, v15, v41
	v_div_fixup_f32 v11, v14, v11, 1.0
	v_div_scale_f32 v14, s[10:11], v10, v10, 1.0
	v_rcp_f32_e32 v15, v14
	v_and_b32_e32 v33, 0xffff0000, v17
	v_pk_add_f32 v[16:17], v[4:5], 1.0 op_sel_hi:[1,0] neg_lo:[1,0] neg_hi:[1,0]
	v_mul_f32_e32 v8, 0xbfb8aa3b, v8
	v_fma_f32 v40, -v14, v15, 1.0
	v_fmac_f32_e32 v15, v40, v15
	v_div_scale_f32 v40, vcc, 1.0, v10, 1.0
	v_mul_f32_e32 v41, v40, v15
	v_fma_f32 v42, -v14, v41, v40
	v_fmac_f32_e32 v41, v42, v15
	v_fma_f32 v14, -v14, v41, v40
	v_div_fmas_f32 v14, v14, v15, v41
	v_div_fixup_f32 v10, v14, v10, 1.0
	v_pk_fma_f32 v[40:41], v[16:17], v[10:11], v[4:5]
	v_mul_f32_e32 v9, 0xbfb8aa3b, v9
	v_cmp_gt_f32_e32 vcc, s78, v40
	v_exp_f32_e32 v8, v8
	v_exp_f32_e32 v9, v9
	v_cndmask_b32_e64 v10, 0, 32, vcc
	v_ldexp_f32 v10, v40, v10
	v_log_f32_e32 v10, v10
	v_pk_add_f32 v[14:15], v[40:41], 1.0 op_sel_hi:[1,0] neg_lo:[1,0] neg_hi:[1,0]
	v_pk_add_f32 v[8:9], v[8:9], 1.0 op_sel_hi:[1,0]
	v_mul_f32_e32 v11, 0x3f317217, v10
	v_fma_f32 v11, v10, s20, -v11
	v_fmac_f32_e32 v11, 0x3377d1cf, v10
	v_fmac_f32_e32 v11, 0x3f317217, v10
	v_cmp_lt_f32_e64 s[42:43], |v10|, s17
	s_nop 1
	v_cndmask_b32_e64 v10, v10, v11, s[42:43]
	v_cndmask_b32_e32 v11, 0, v203, vcc
	v_cmp_gt_f32_e32 vcc, s78, v41
	v_sub_f32_e32 v10, v10, v11
	s_nop 0
	v_cndmask_b32_e64 v11, 0, 32, vcc
	v_ldexp_f32 v11, v41, v11
	v_log_f32_e32 v11, v11
	s_nop 0
	v_mul_f32_e32 v40, 0x3f317217, v11
	v_fma_f32 v40, v11, s20, -v40
	v_fmac_f32_e32 v40, 0x3377d1cf, v11
	v_fmac_f32_e32 v40, 0x3f317217, v11
	v_cmp_lt_f32_e64 s[42:43], |v11|, s17
	s_nop 1
	v_cndmask_b32_e64 v11, v11, v40, s[42:43]
	v_cndmask_b32_e32 v40, 0, v203, vcc
	v_sub_f32_e32 v11, v11, v40
	v_div_scale_f32 v40, s[10:11], v9, v9, 1.0
	v_rcp_f32_e32 v41, v40
	s_nop 0
	v_fma_f32 v42, -v40, v41, 1.0
	v_fmac_f32_e32 v41, v42, v41
	v_div_scale_f32 v42, vcc, 1.0, v9, 1.0
	v_mul_f32_e32 v43, v42, v41
	v_fma_f32 v44, -v40, v43, v42
	v_fmac_f32_e32 v43, v44, v41
	v_fma_f32 v40, -v40, v43, v42
	v_div_fmas_f32 v40, v40, v41, v43
	v_div_fixup_f32 v9, v40, v9, 1.0
	v_div_scale_f32 v40, s[10:11], v8, v8, 1.0
	v_rcp_f32_e32 v41, v40
	s_nop 0
	v_fma_f32 v42, -v40, v41, 1.0
	v_fmac_f32_e32 v41, v42, v41
	v_div_scale_f32 v42, vcc, 1.0, v8, 1.0
	v_mul_f32_e32 v43, v42, v41
	v_fma_f32 v44, -v40, v43, v42
	v_fmac_f32_e32 v43, v44, v41
	v_fma_f32 v40, -v40, v43, v42
	v_div_fmas_f32 v40, v40, v41, v43
	v_div_fixup_f32 v8, v40, v8, 1.0
	v_pk_fma_f32 v[16:17], v[16:17], v[8:9], v[4:5]
	s_nop 0
	v_cmp_gt_f32_e32 vcc, s78, v16
	v_pk_add_f32 v[8:9], v[16:17], 1.0 op_sel_hi:[1,0] neg_lo:[1,0] neg_hi:[1,0]
	s_nop 0
	v_cndmask_b32_e64 v4, 0, 32, vcc
	v_ldexp_f32 v4, v16, v4
	v_log_f32_e32 v4, v4
	s_nop 0
	v_mul_f32_e32 v5, 0x3f317217, v4
	v_fma_f32 v5, v4, s20, -v5
	v_fmac_f32_e32 v5, 0x3377d1cf, v4
	v_fmac_f32_e32 v5, 0x3f317217, v4
	v_cmp_lt_f32_e64 s[42:43], |v4|, s17
	s_nop 1
	v_cndmask_b32_e64 v4, v4, v5, s[42:43]
	v_cndmask_b32_e32 v5, 0, v203, vcc
	v_cmp_gt_f32_e32 vcc, s78, v17
	v_sub_f32_e32 v4, v4, v5
	s_nop 0
	v_cndmask_b32_e64 v5, 0, 32, vcc
	v_ldexp_f32 v5, v17, v5
	v_log_f32_e32 v5, v5
	s_nop 0
	v_mul_f32_e32 v16, 0x3f317217, v5
	v_fma_f32 v16, v5, s20, -v16
	v_fmac_f32_e32 v16, 0x3377d1cf, v5
	v_fmac_f32_e32 v16, 0x3f317217, v5
	v_cmp_lt_f32_e64 s[42:43], |v5|, s17
	s_nop 1
	v_cndmask_b32_e64 v5, v5, v16, s[42:43]
	v_cndmask_b32_e32 v16, 0, v203, vcc
	v_sub_f32_e32 v5, v5, v16
	v_mul_f32_e32 v16, 0xbfb8aa3b, v35
	v_exp_f32_e32 v40, v16
	v_mul_f32_e32 v16, 0xbfb8aa3b, v34
	v_exp_f32_e32 v41, v16
	v_div_scale_f32 v16, s[10:11], v13, v13, 1.0
	v_rcp_f32_e32 v17, v16
	v_pk_add_f32 v[34:35], v[6:7], 1.0 op_sel_hi:[1,0] neg_lo:[1,0] neg_hi:[1,0]
	v_fma_f32 v42, -v16, v17, 1.0
	v_fmac_f32_e32 v17, v42, v17
	v_div_scale_f32 v42, vcc, 1.0, v13, 1.0
	v_mul_f32_e32 v43, v42, v17
	v_fma_f32 v44, -v16, v43, v42
	v_fmac_f32_e32 v43, v44, v17
	v_fma_f32 v16, -v16, v43, v42
	v_div_fmas_f32 v16, v16, v17, v43
	v_div_fixup_f32 v13, v16, v13, 1.0
	v_div_scale_f32 v16, s[10:11], v12, v12, 1.0
	v_rcp_f32_e32 v17, v16
	s_nop 0
	v_fma_f32 v42, -v16, v17, 1.0
	v_fmac_f32_e32 v17, v42, v17
	v_div_scale_f32 v42, vcc, 1.0, v12, 1.0
	v_mul_f32_e32 v43, v42, v17
	v_fma_f32 v44, -v16, v43, v42
	v_fmac_f32_e32 v43, v44, v17
	v_fma_f32 v16, -v16, v43, v42
	v_div_fmas_f32 v16, v16, v17, v43
	v_div_fixup_f32 v12, v16, v12, 1.0
	v_pk_fma_f32 v[42:43], v[34:35], v[12:13], v[6:7]
	s_nop 0
	v_cmp_gt_f32_e32 vcc, s78, v42
	v_pk_add_f32 v[16:17], v[42:43], 1.0 op_sel_hi:[1,0] neg_lo:[1,0] neg_hi:[1,0]
	ds_write_b128 v31, v[14:17]
	v_cndmask_b32_e64 v12, 0, 32, vcc
	v_ldexp_f32 v12, v42, v12
	v_log_f32_e32 v12, v12
	s_nop 0
	v_mul_f32_e32 v13, 0x3f317217, v12
	v_fma_f32 v13, v12, s20, -v13
	v_fmac_f32_e32 v13, 0x3377d1cf, v12
	v_fmac_f32_e32 v13, 0x3f317217, v12
	v_cmp_lt_f32_e64 s[42:43], |v12|, s17
	s_nop 1
	v_cndmask_b32_e64 v12, v12, v13, s[42:43]
	v_cndmask_b32_e32 v13, 0, v203, vcc
	v_cmp_gt_f32_e32 vcc, s78, v43
	v_sub_f32_e32 v12, v12, v13
	s_nop 0
	v_cndmask_b32_e64 v13, 0, 32, vcc
	v_ldexp_f32 v13, v43, v13
	v_log_f32_e32 v13, v13
	s_nop 0
	v_mul_f32_e32 v14, 0x3f317217, v13
	v_fma_f32 v14, v13, s20, -v14
	v_fmac_f32_e32 v14, 0x3377d1cf, v13
	v_fmac_f32_e32 v14, 0x3f317217, v13
	v_cmp_lt_f32_e64 s[42:43], |v13|, s17
	s_nop 1
	v_cndmask_b32_e64 v13, v13, v14, s[42:43]
	v_cndmask_b32_e32 v14, 0, v203, vcc
	v_sub_f32_e32 v13, v13, v14
	ds_write_b128 v27, v[10:13]
	v_pk_add_f32 v[10:11], v[40:41], 1.0 op_sel_hi:[1,0]
	s_nop 0
	v_div_scale_f32 v12, s[10:11], v11, v11, 1.0
	v_rcp_f32_e32 v13, v12
	s_nop 0
	v_fma_f32 v14, -v12, v13, 1.0
	v_fmac_f32_e32 v13, v14, v13
	v_div_scale_f32 v14, vcc, 1.0, v11, 1.0
	v_mul_f32_e32 v15, v14, v13
	v_fma_f32 v16, -v12, v15, v14
	v_fmac_f32_e32 v15, v16, v13
	v_fma_f32 v12, -v12, v15, v14
	v_div_fmas_f32 v12, v12, v13, v15
	v_div_fixup_f32 v11, v12, v11, 1.0
	v_div_scale_f32 v12, s[10:11], v10, v10, 1.0
	v_rcp_f32_e32 v13, v12
	s_nop 0
	v_fma_f32 v14, -v12, v13, 1.0
	v_fmac_f32_e32 v13, v14, v13
	v_div_scale_f32 v14, vcc, 1.0, v10, 1.0
	v_mul_f32_e32 v15, v14, v13
	v_fma_f32 v16, -v12, v15, v14
	v_fmac_f32_e32 v15, v16, v13
	v_fma_f32 v12, -v12, v15, v14
	v_div_fmas_f32 v12, v12, v13, v15
	v_div_fixup_f32 v10, v12, v10, 1.0
	v_pk_fma_f32 v[12:13], v[34:35], v[10:11], v[6:7]
	v_pk_add_f32 v[14:15], v[0:1], 1.0 op_sel_hi:[1,0] neg_lo:[1,0] neg_hi:[1,0]
	v_cmp_gt_f32_e32 vcc, s78, v12
	v_pk_add_f32 v[10:11], v[12:13], 1.0 op_sel_hi:[1,0] neg_lo:[1,0] neg_hi:[1,0]
	s_nop 0
	v_cndmask_b32_e64 v6, 0, 32, vcc
	v_ldexp_f32 v6, v12, v6
	v_log_f32_e32 v6, v6
	s_nop 0
	v_mul_f32_e32 v7, 0x3f317217, v6
	v_fma_f32 v7, v6, s20, -v7
	v_fmac_f32_e32 v7, 0x3377d1cf, v6
	v_fmac_f32_e32 v7, 0x3f317217, v6
	v_cmp_lt_f32_e64 s[42:43], |v6|, s17
	s_nop 1
	v_cndmask_b32_e64 v6, v6, v7, s[42:43]
	v_cndmask_b32_e32 v7, 0, v203, vcc
	v_cmp_gt_f32_e32 vcc, s78, v13
	v_sub_f32_e32 v6, v6, v7
	s_nop 0
	v_cndmask_b32_e64 v7, 0, 32, vcc
	v_ldexp_f32 v7, v13, v7
	v_log_f32_e32 v7, v7
	s_nop 0
	v_mul_f32_e32 v12, 0x3f317217, v7
	v_fma_f32 v12, v7, s20, -v12
	v_fmac_f32_e32 v12, 0x3377d1cf, v7
	v_fmac_f32_e32 v12, 0x3f317217, v7
	v_cmp_lt_f32_e64 s[42:43], |v7|, s17
	s_nop 1
	v_cndmask_b32_e64 v7, v7, v12, s[42:43]
	v_cndmask_b32_e32 v12, 0, v203, vcc
	v_sub_f32_e32 v7, v7, v12
	v_mul_f32_e32 v12, 0xbfb8aa3b, v39
	v_exp_f32_e32 v16, v12
	v_mul_f32_e32 v12, 0xbfb8aa3b, v38
	v_exp_f32_e32 v17, v12
	v_pk_add_f32 v[12:13], v[18:19], 1.0 op_sel_hi:[1,0]
	v_pk_add_f32 v[16:17], v[16:17], 1.0 op_sel_hi:[1,0]
	v_div_scale_f32 v18, s[10:11], v13, v13, 1.0
	v_rcp_f32_e32 v19, v18
	s_nop 0
	v_fma_f32 v34, -v18, v19, 1.0
	v_fmac_f32_e32 v19, v34, v19
	v_div_scale_f32 v34, vcc, 1.0, v13, 1.0
	v_mul_f32_e32 v35, v34, v19
	v_fma_f32 v38, -v18, v35, v34
	v_fmac_f32_e32 v35, v38, v19
	v_fma_f32 v18, -v18, v35, v34
	v_div_fmas_f32 v18, v18, v19, v35
	v_div_fixup_f32 v13, v18, v13, 1.0
	v_div_scale_f32 v18, s[10:11], v12, v12, 1.0
	v_rcp_f32_e32 v19, v18
	s_nop 0
	v_fma_f32 v34, -v18, v19, 1.0
	v_fmac_f32_e32 v19, v34, v19
	v_div_scale_f32 v34, vcc, 1.0, v12, 1.0
	v_mul_f32_e32 v35, v34, v19
	v_fma_f32 v38, -v18, v35, v34
	v_fmac_f32_e32 v35, v38, v19
	v_fma_f32 v18, -v18, v35, v34
	v_div_fmas_f32 v18, v18, v19, v35
	v_div_fixup_f32 v12, v18, v12, 1.0
	v_pk_fma_f32 v[34:35], v[14:15], v[12:13], v[0:1]
	s_nop 0
	v_cmp_gt_f32_e32 vcc, s78, v34
	v_pk_add_f32 v[18:19], v[34:35], 1.0 op_sel_hi:[1,0] neg_lo:[1,0] neg_hi:[1,0]
	s_nop 0
	v_cndmask_b32_e64 v12, 0, 32, vcc
	v_ldexp_f32 v12, v34, v12
	v_log_f32_e32 v12, v12
	s_nop 0
	v_mul_f32_e32 v13, 0x3f317217, v12
	v_fma_f32 v13, v12, s20, -v13
	v_fmac_f32_e32 v13, 0x3377d1cf, v12
	v_fmac_f32_e32 v13, 0x3f317217, v12
	v_cmp_lt_f32_e64 s[42:43], |v12|, s17
	s_nop 1
	v_cndmask_b32_e64 v12, v12, v13, s[42:43]
	v_cndmask_b32_e32 v13, 0, v203, vcc
	v_cmp_gt_f32_e32 vcc, s78, v35
	v_sub_f32_e32 v12, v12, v13
	s_nop 0
	v_cndmask_b32_e64 v13, 0, 32, vcc
	v_ldexp_f32 v13, v35, v13
	v_log_f32_e32 v13, v13
	s_nop 0
	v_mul_f32_e32 v34, 0x3f317217, v13
	v_fma_f32 v34, v13, s20, -v34
	v_fmac_f32_e32 v34, 0x3377d1cf, v13
	v_fmac_f32_e32 v34, 0x3f317217, v13
	v_cmp_lt_f32_e64 s[42:43], |v13|, s17
	s_nop 1
	v_cndmask_b32_e64 v13, v13, v34, s[42:43]
	v_cndmask_b32_e32 v34, 0, v203, vcc
	v_sub_f32_e32 v13, v13, v34
	v_div_scale_f32 v34, s[10:11], v17, v17, 1.0
	v_rcp_f32_e32 v35, v34
	s_nop 0
	v_fma_f32 v38, -v34, v35, 1.0
	v_fmac_f32_e32 v35, v38, v35
	v_div_scale_f32 v38, vcc, 1.0, v17, 1.0
	v_mul_f32_e32 v39, v38, v35
	v_fma_f32 v40, -v34, v39, v38
	v_fmac_f32_e32 v39, v40, v35
	v_fma_f32 v34, -v34, v39, v38
	v_div_fmas_f32 v34, v34, v35, v39
	v_div_fixup_f32 v17, v34, v17, 1.0
	v_div_scale_f32 v34, s[10:11], v16, v16, 1.0
	v_rcp_f32_e32 v35, v34
	s_nop 0
	v_fma_f32 v38, -v34, v35, 1.0
	v_fmac_f32_e32 v35, v38, v35
	v_div_scale_f32 v38, vcc, 1.0, v16, 1.0
	v_mul_f32_e32 v39, v38, v35
	v_fma_f32 v40, -v34, v39, v38
	v_fmac_f32_e32 v39, v40, v35
	v_fma_f32 v34, -v34, v39, v38
	v_div_fmas_f32 v34, v34, v35, v39
	v_div_fixup_f32 v16, v34, v16, 1.0
	v_pk_fma_f32 v[14:15], v[14:15], v[16:17], v[0:1]
	v_pk_add_f32 v[34:35], v[2:3], 1.0 op_sel_hi:[1,0] neg_lo:[1,0] neg_hi:[1,0]
	v_cmp_gt_f32_e32 vcc, s78, v14
	v_pk_add_f32 v[16:17], v[14:15], 1.0 op_sel_hi:[1,0] neg_lo:[1,0] neg_hi:[1,0]
	s_nop 0
	v_cndmask_b32_e64 v0, 0, 32, vcc
	v_ldexp_f32 v0, v14, v0
	v_log_f32_e32 v0, v0
	s_nop 0
	v_mul_f32_e32 v1, 0x3f317217, v0
	v_fma_f32 v1, v0, s20, -v1
	v_fmac_f32_e32 v1, 0x3377d1cf, v0
	v_fmac_f32_e32 v1, 0x3f317217, v0
	v_cmp_lt_f32_e64 s[42:43], |v0|, s17
	s_nop 1
	v_cndmask_b32_e64 v0, v0, v1, s[42:43]
	v_cndmask_b32_e32 v1, 0, v203, vcc
	v_cmp_gt_f32_e32 vcc, s78, v15
	v_sub_f32_e32 v0, v0, v1
	s_nop 0
	v_cndmask_b32_e64 v1, 0, 32, vcc
	v_ldexp_f32 v1, v15, v1
	v_log_f32_e32 v1, v1
	s_nop 0
	v_mul_f32_e32 v14, 0x3f317217, v1
	v_fma_f32 v14, v1, s20, -v14
	v_fmac_f32_e32 v14, 0x3377d1cf, v1
	v_fmac_f32_e32 v14, 0x3f317217, v1
	v_cmp_lt_f32_e64 s[42:43], |v1|, s17
	s_nop 1
	v_cndmask_b32_e64 v1, v1, v14, s[42:43]
	v_cndmask_b32_e32 v14, 0, v203, vcc
	v_sub_f32_e32 v1, v1, v14
	v_mul_f32_e32 v14, 0xbfb8aa3b, v37
	v_exp_f32_e32 v38, v14
	v_mul_f32_e32 v14, 0xbfb8aa3b, v33
	v_exp_f32_e32 v39, v14
	v_pk_add_f32 v[14:15], v[20:21], 1.0 op_sel_hi:[1,0]
	s_nop 0
	v_div_scale_f32 v20, s[10:11], v15, v15, 1.0
	v_rcp_f32_e32 v21, v20
	s_nop 0
	v_fma_f32 v33, -v20, v21, 1.0
	v_fmac_f32_e32 v21, v33, v21
	v_div_scale_f32 v33, vcc, 1.0, v15, 1.0
	v_mul_f32_e32 v37, v33, v21
	v_fma_f32 v40, -v20, v37, v33
	v_fmac_f32_e32 v37, v40, v21
	v_fma_f32 v20, -v20, v37, v33
	v_div_fmas_f32 v20, v20, v21, v37
	v_div_fixup_f32 v15, v20, v15, 1.0
	v_div_scale_f32 v20, s[10:11], v14, v14, 1.0
	v_rcp_f32_e32 v21, v20
	s_nop 0
	v_fma_f32 v33, -v20, v21, 1.0
	v_fmac_f32_e32 v21, v33, v21
	v_div_scale_f32 v33, vcc, 1.0, v14, 1.0
	v_mul_f32_e32 v37, v33, v21
	v_fma_f32 v40, -v20, v37, v33
	v_fmac_f32_e32 v37, v40, v21
	v_fma_f32 v20, -v20, v37, v33
	v_div_fmas_f32 v20, v20, v21, v37
	v_div_fixup_f32 v14, v20, v14, 1.0
	v_pk_fma_f32 v[40:41], v[34:35], v[14:15], v[2:3]
	s_nop 0
	v_cmp_gt_f32_e32 vcc, s78, v40
	v_pk_add_f32 v[20:21], v[40:41], 1.0 op_sel_hi:[1,0] neg_lo:[1,0] neg_hi:[1,0]
	ds_write_b128 v31, v[18:21] offset:16
	v_cndmask_b32_e64 v14, 0, 32, vcc
	v_ldexp_f32 v14, v40, v14
	v_log_f32_e32 v14, v14
	s_nop 0
	v_mul_f32_e32 v15, 0x3f317217, v14
	v_fma_f32 v15, v14, s20, -v15
	v_fmac_f32_e32 v15, 0x3377d1cf, v14
	v_fmac_f32_e32 v15, 0x3f317217, v14
	v_cmp_lt_f32_e64 s[42:43], |v14|, s17
	s_nop 1
	v_cndmask_b32_e64 v14, v14, v15, s[42:43]
	v_cndmask_b32_e32 v15, 0, v203, vcc
	v_cmp_gt_f32_e32 vcc, s78, v41
	v_sub_f32_e32 v14, v14, v15
	s_nop 0
	v_cndmask_b32_e64 v15, 0, 32, vcc
	v_ldexp_f32 v15, v41, v15
	v_log_f32_e32 v15, v15
	s_nop 0
	v_mul_f32_e32 v18, 0x3f317217, v15
	v_fma_f32 v18, v15, s20, -v18
	v_fmac_f32_e32 v18, 0x3377d1cf, v15
	v_fmac_f32_e32 v18, 0x3f317217, v15
	v_cmp_lt_f32_e64 s[42:43], |v15|, s17
	s_nop 1
	v_cndmask_b32_e64 v15, v15, v18, s[42:43]
	v_cndmask_b32_e32 v18, 0, v203, vcc
	v_sub_f32_e32 v15, v15, v18
	ds_write_b128 v27, v[12:15] offset:16
	ds_write_b128 v29, v[8:11]
	ds_write_b128 v25, v[4:7]
	v_pk_add_f32 v[4:5], v[38:39], 1.0 op_sel_hi:[1,0]
	s_nop 0
	v_div_scale_f32 v6, s[10:11], v5, v5, 1.0
	v_rcp_f32_e32 v7, v6
	s_nop 0
	v_fma_f32 v8, -v6, v7, 1.0
	v_fmac_f32_e32 v7, v8, v7
	v_div_scale_f32 v8, vcc, 1.0, v5, 1.0
	v_mul_f32_e32 v9, v8, v7
	v_fma_f32 v10, -v6, v9, v8
	v_fmac_f32_e32 v9, v10, v7
	v_fma_f32 v6, -v6, v9, v8
	v_div_fmas_f32 v6, v6, v7, v9
	v_div_fixup_f32 v5, v6, v5, 1.0
	v_div_scale_f32 v6, s[10:11], v4, v4, 1.0
	v_rcp_f32_e32 v7, v6
	s_nop 0
	v_fma_f32 v8, -v6, v7, 1.0
	v_fmac_f32_e32 v7, v8, v7
	v_div_scale_f32 v8, vcc, 1.0, v4, 1.0
	v_mul_f32_e32 v9, v8, v7
	v_fma_f32 v10, -v6, v9, v8
	v_fmac_f32_e32 v9, v10, v7
	v_fma_f32 v6, -v6, v9, v8
	v_div_fmas_f32 v6, v6, v7, v9
	v_div_fixup_f32 v4, v6, v4, 1.0
	v_pk_fma_f32 v[4:5], v[34:35], v[4:5], v[2:3]
	s_nop 0
	v_cmp_gt_f32_e32 vcc, s78, v4
	v_pk_add_f32 v[18:19], v[4:5], 1.0 op_sel_hi:[1,0] neg_lo:[1,0] neg_hi:[1,0]
	ds_write_b128 v29, v[16:19] offset:16
	v_cndmask_b32_e64 v2, 0, 32, vcc
	v_ldexp_f32 v2, v4, v2
	v_log_f32_e32 v2, v2
	s_nop 0
	v_mul_f32_e32 v3, 0x3f317217, v2
	v_fma_f32 v3, v2, s20, -v3
	v_fmac_f32_e32 v3, 0x3377d1cf, v2
	v_fmac_f32_e32 v3, 0x3f317217, v2
	v_cmp_lt_f32_e64 s[42:43], |v2|, s17
	s_nop 1
	v_cndmask_b32_e64 v2, v2, v3, s[42:43]
	v_cndmask_b32_e32 v3, 0, v203, vcc
	v_cmp_gt_f32_e32 vcc, s78, v5
	v_sub_f32_e32 v2, v2, v3
	s_nop 0
	v_cndmask_b32_e64 v3, 0, 32, vcc
	v_ldexp_f32 v3, v5, v3
	v_log_f32_e32 v3, v3
	s_nop 0
	v_mul_f32_e32 v4, 0x3f317217, v3
	v_fma_f32 v4, v3, s20, -v4
	v_fmac_f32_e32 v4, 0x3377d1cf, v3
	v_fmac_f32_e32 v4, 0x3f317217, v3
	v_cmp_lt_f32_e64 s[42:43], |v3|, s17
	s_nop 1
	v_cndmask_b32_e64 v3, v3, v4, s[42:43]
	v_cndmask_b32_e32 v4, 0, v203, vcc
	v_sub_f32_e32 v3, v3, v4
	v_cmp_gt_i32_e32 vcc, s6, v36
	ds_write_b128 v25, v[0:3] offset:16
	s_and_saveexec_b64 s[42:43], vcc
	s_cbranch_execz .LBB0_726
	v_and_b32_e32 v2, 63, v36
	v_or_b32_e32 v3, s54, v2
	v_mov_b64_e32 v[0:1], s[48:49]
	v_mad_u64_u32 v[0:1], s[10:11], v3, s13, v[0:1]
	v_mad_i32_i24 v1, s55, v204, v1
	s_mul_i32 s60, s53, 0xc0
	v_lshl_add_u64 v[0:1], v[0:1], 0, s[60:61]
	s_mov_b64 s[10:11], 0x1400
	v_lshl_add_u64 v[0:1], v[0:1], 0, s[10:11]
	v_lshl_add_u32 v2, v2, 1, 0
	s_mov_b64 s[54:55], 0
	v_mov_b32_e32 v3, v36
	s_waitcnt vmcnt(0)
.LBB0_725:
	v_ashrrev_i32_e32 v4, 3, v3
	v_and_b32_e32 v8, -8, v4
	v_ashrrev_i32_e32 v9, 31, v8
	v_lshl_add_u64 v[4:5], v[8:9], 1, v[0:1]
	v_mov_b32_e32 v4, v110
	v_mov_b32_e32 v5, v111
	v_mov_b32_e32 v6, v112
	v_mov_b32_e32 v7, v113
	v_add_u32_e32 v9, 0x200, v3
	v_cmp_lt_i32_e32 vcc, s67, v3
	v_mov_b32_e32 v3, v9
	s_or_b64 s[54:55], vcc, s[54:55]
	v_mad_u64_u32 v[8:9], s[10:11], v8, s21, v[2:3]
	ds_write_b16 v8, v4 offset:51200
	ds_write_b16_d16_hi v8, v4 offset:51344
	ds_write_b16 v8, v5 offset:51488
	ds_write_b16_d16_hi v8, v5 offset:51632
	ds_write_b16 v8, v6 offset:51776
	ds_write_b16_d16_hi v8, v6 offset:51920
	ds_write_b16 v8, v7 offset:52064
	ds_write_b16_d16_hi v8, v7 offset:52208
	v_mov_b32_e32 v110, v114
	v_mov_b32_e32 v111, v115
	v_mov_b32_e32 v112, v116
	v_mov_b32_e32 v113, v117
	s_andn2_b64 exec, exec, s[54:55]
	s_cbranch_execnz .LBB0_725

.LBB0_732:
	s_lshl_b32 s58, s77, 1
	s_add_i32 s58, s58, s86
	s_ashr_i32 s42, s58, 2
	s_ashr_i32 s43, s42, 31
	v_mov_b32_e32 v16, v186
	s_and_b32 s10, s58, 3
	s_lshl_b64 s[52:53], s[42:43], 6
	s_movk_i32 s11, 0x300
	v_and_b32_e32 v18, 63, v16
	s_mul_i32 s6, s10, 0x60
	v_cmp_gt_i32_e32 vcc, s11, v16
	v_or_b32_e32 v4, s52, v18
	s_and_saveexec_b64 s[42:43], vcc
	s_cbranch_execz .LBB0_735
	v_mov_b64_e32 v[0:1], s[48:49]
	v_mad_u64_u32 v[0:1], s[54:55], v4, s13, v[0:1]
	v_mad_i32_i24 v1, s53, v204, v1
	s_lshl_b32 s60, s6, 1
	v_lshl_add_u64 v[0:1], v[0:1], 0, s[60:61]
	v_lshl_add_u32 v2, v18, 1, 0
	s_mov_b64 s[54:55], 0
	v_mov_b32_e32 v3, v16
	v_lshrrev_b32_e32 v104, 6, v16
	v_lshlrev_b32_e32 v104, 4, v104
	v_mov_b32_e32 v105, 0
	v_lshl_add_u64 v[102:103], v[0:1], 0, v[104:105]
	global_load_dwordx4 v[110:113], v[102:103], off offset:1536
	global_load_dwordx4 v[114:117], v[102:103], off offset:1664
	s_waitcnt vmcnt(0)
.LBB0_734:
	v_ashrrev_i32_e32 v5, 3, v3
	v_and_b32_e32 v10, -8, v5
	v_ashrrev_i32_e32 v11, 31, v10
	v_lshl_add_u64 v[6:7], v[10:11], 1, v[0:1]
	v_mov_b32_e32 v6, v110
	v_mov_b32_e32 v7, v111
	v_mov_b32_e32 v8, v112
	v_mov_b32_e32 v9, v113
	v_add_u32_e32 v5, 0x200, v3
	v_cmp_lt_i32_e32 vcc, s67, v3
	v_mov_b32_e32 v3, v5
	s_or_b64 s[54:55], vcc, s[54:55]
	v_mad_u64_u32 v[10:11], s[70:71], v10, s21, v[2:3]
	ds_write_b16 v10, v6 offset:51200
	ds_write_b16_d16_hi v10, v6 offset:51344
	ds_write_b16 v10, v7 offset:51488
	ds_write_b16_d16_hi v10, v7 offset:51632
	ds_write_b16 v10, v8 offset:51776
	ds_write_b16_d16_hi v10, v8 offset:51920
	ds_write_b16 v10, v9 offset:52064
	ds_write_b16_d16_hi v10, v9 offset:52208
	v_mov_b32_e32 v110, v114
	v_mov_b32_e32 v111, v115
	v_mov_b32_e32 v112, v116
	v_mov_b32_e32 v113, v117
	s_andn2_b64 exec, exec, s[54:55]
	s_cbranch_execnz .LBB0_734
